# grid barrier: the acquire-side L1 invalidate is issued by wave 1 at barrier entry (overlapping the arrive/poll of wave 0) instead of by thread 0 after the release
# speedup vs baseline: 1.0155x; 1.0006x over previous
.LBB0_37:
	s_waitcnt vmcnt(0)
	s_waitcnt lgkmcnt(0)
	s_barrier
	s_mov_b64 s[4:5], exec
	v_readlane_b32 s2, v255, 4
	v_readlane_b32 s3, v255, 5
	s_and_b64 s[2:3], s[4:5], s[2:3]
	s_mov_b64 exec, s[2:3]
	s_cbranch_execnz .Lmy_bar0_t0
	s_cmp_eq_u32 s33, 64
	s_cbranch_scc0 .LBB0_89
	s_mov_b64 exec, 1
	buffer_inv sc1
	s_waitcnt vmcnt(0)
	s_branch .LBB0_89
.Lmy_bar0_t0:
	s_add_i32 s1, 0, 0x25400
	v_mov_b32_e32 v0, s1
	s_waitcnt vmcnt(0) expcnt(0) lgkmcnt(0)
	ds_read_b32 v2, v0
	s_add_i32 s1, 0, 0x25404
	v_mov_b32_e32 v0, s1
	ds_read_b32 v0, v0
	s_waitcnt lgkmcnt(1)
	v_cmp_ne_u32_e32 vcc, 0, v2
	s_cbranch_vccnz .LBB0_53
	v_readlane_b32 s6, v255, 0
	v_readlane_b32 s7, v255, 1
	s_load_dwordx2 s[2:3], s[6:7], 0x4
	s_add_u32 s6, s82, 0x1000
	s_addc_u32 s7, s83, 0
	s_add_u32 s8, s82, 0x1100
	s_addc_u32 s9, s83, 0
	s_add_u32 s14, s82, 0x1200
	s_addc_u32 s15, s83, 0
	s_waitcnt lgkmcnt(0)
	s_mul_i32 s1, s2, s0
	s_add_u32 s16, s82, 0x1300
	s_mul_i32 s1, s1, s3
	s_addc_u32 s17, s83, 0
	s_mov_b32 s2, 1
	v_mov_b32_e32 v16, 0
	s_branch .LBB0_41

.LBB0_68:
	s_or_b64 exec, exec, s[14:15]
	s_waitcnt vmcnt(0)
	s_waitcnt vmcnt(0)

.LBB0_86:
	s_or_b64 exec, exec, s[8:9]
	s_mov_b64 s[8:9], exec
	v_mbcnt_lo_u32_b32 v0, s8, 0
	v_mbcnt_hi_u32_b32 v0, s9, v0
	v_cmp_eq_u32_e32 vcc, 0, v0
	s_waitcnt vmcnt(0)
	s_and_saveexec_b64 s[14:15], vcc
	s_cbranch_execz .LBB0_88
	s_bcnt1_i32_b64 s1, s[8:9]
	v_mov_b32_e32 v0, 0x2000
	v_mov_b32_e32 v1, s1
	global_atomic_add v0, v1, s[6:7] offset:1024

.LBB0_184:
	s_waitcnt vmcnt(0)
	s_waitcnt vmcnt(0) lgkmcnt(0)
	s_barrier
	s_mov_b64 s[4:5], exec
	v_readlane_b32 s2, v255, 4
	v_readlane_b32 s3, v255, 5
	s_and_b64 s[2:3], s[4:5], s[2:3]
	s_mov_b64 exec, s[2:3]
	s_cbranch_execnz .Lmy_bar1_t0
	s_cmp_eq_u32 s33, 64
	s_cbranch_scc0 .LBB0_236
	s_mov_b64 exec, 1
	buffer_inv sc1
	s_waitcnt vmcnt(0)
	s_branch .LBB0_236
.Lmy_bar1_t0:
	s_add_i32 s1, 0, 0x25400
	v_mov_b32_e32 v0, s1
	s_waitcnt vmcnt(0) expcnt(0) lgkmcnt(0)
	ds_read_b32 v2, v0
	s_add_i32 s1, 0, 0x25404
	v_mov_b32_e32 v0, s1
	ds_read_b32 v0, v0
	s_waitcnt lgkmcnt(1)
	v_cmp_ne_u32_e32 vcc, 0, v2
	s_cbranch_vccnz .LBB0_200
	v_readlane_b32 s6, v255, 0
	v_readlane_b32 s7, v255, 1
	s_load_dwordx2 s[2:3], s[6:7], 0x4
	s_add_u32 s6, s82, 0x1000
	s_addc_u32 s7, s83, 0
	s_add_u32 s8, s82, 0x1100
	s_addc_u32 s9, s83, 0
	s_add_u32 s10, s82, 0x1200
	s_addc_u32 s11, s83, 0
	s_waitcnt lgkmcnt(0)
	s_mul_i32 s1, s2, s0
	s_add_u32 s12, s82, 0x1300
	s_mul_i32 s1, s1, s3
	s_addc_u32 s13, s83, 0
	s_mov_b32 s2, 1
	v_mov_b32_e32 v16, 0
	s_branch .LBB0_188

.LBB0_215:
	s_or_b64 exec, exec, s[10:11]
	s_waitcnt vmcnt(0)
	s_waitcnt vmcnt(0)

.LBB0_233:
	s_or_b64 exec, exec, s[8:9]
	s_mov_b64 s[8:9], exec
	v_mbcnt_lo_u32_b32 v0, s8, 0
	v_mbcnt_hi_u32_b32 v0, s9, v0
	v_cmp_eq_u32_e32 vcc, 0, v0
	s_waitcnt vmcnt(0)
	s_and_saveexec_b64 s[10:11], vcc
	s_cbranch_execz .LBB0_235
	s_bcnt1_i32_b64 s1, s[8:9]
	v_mov_b32_e32 v0, 0x2000
	v_mov_b32_e32 v1, s1
	global_atomic_add v0, v1, s[6:7] offset:1024

.LBB0_310:
	s_waitcnt vmcnt(0)
	s_waitcnt lgkmcnt(0)
	s_barrier
	s_mov_b64 s[4:5], exec
	v_readlane_b32 s2, v255, 4
	v_readlane_b32 s3, v255, 5
	v_readlane_b32 s62, v255, 26
	s_and_b64 s[2:3], s[4:5], s[2:3]
	v_readlane_b32 s64, v255, 30
	v_readlane_b32 s63, v255, 27
	s_mov_b64 exec, s[2:3]
	s_cbranch_execnz .Lmy_bar2_t0
	s_cmp_eq_u32 s33, 64
	s_cbranch_scc0 .LBB0_362
	s_mov_b64 exec, 1
	buffer_inv sc1
	s_waitcnt vmcnt(0)
	s_branch .LBB0_362

.LBB0_492:
	s_or_b64 exec, exec, s[4:5]
	s_waitcnt vmcnt(0)
	s_waitcnt lgkmcnt(0)
	s_barrier
	s_mov_b64 s[4:5], exec
	v_readlane_b32 s2, v255, 4
	v_readlane_b32 s3, v255, 5
	s_and_b64 s[2:3], s[4:5], s[2:3]
	s_mov_b64 exec, s[2:3]
	s_cbranch_execnz .Lmy_bar4_t0
	s_cmp_eq_u32 s33, 64
	s_cbranch_scc0 .LBB0_544
	s_mov_b64 exec, 1
	buffer_inv sc1
	s_waitcnt vmcnt(0)
	s_branch .LBB0_544

.LBB0_793:
	v_writelane_b32 v255, s56, 7
	s_nop 1
	v_writelane_b32 v255, s57, 8
	s_or_b64 exec, exec, s[4:5]
	s_waitcnt vmcnt(0)
	s_waitcnt lgkmcnt(0)
	s_barrier
	s_mov_b64 s[4:5], exec
	v_readlane_b32 s2, v255, 4
	v_readlane_b32 s3, v255, 5
	s_and_b64 s[2:3], s[4:5], s[2:3]
	s_mov_b64 exec, s[2:3]
	s_cbranch_execnz .Lmy_bar7_t0
	s_cmp_eq_u32 s33, 64
	s_cbranch_scc0 .LBB0_845
	s_mov_b64 exec, 1
	buffer_inv sc1
	s_waitcnt vmcnt(0)
	s_branch .LBB0_845

.LBB0_1066:
	s_waitcnt vmcnt(0)
	s_barrier
	s_mov_b64 s[4:5], exec
	v_readlane_b32 s2, v255, 4
	v_readlane_b32 s3, v255, 5
	s_and_b64 s[2:3], s[4:5], s[2:3]
	s_mov_b64 exec, s[2:3]
	s_cbranch_execnz .Lmy_bar9_t0
	s_cmp_eq_u32 s33, 64
	s_cbranch_scc0 .LBB0_1118
	s_mov_b64 exec, 1
	buffer_inv sc1
	s_waitcnt vmcnt(0)
	s_branch .LBB0_1118

.Lmy_bar12_t0:
	s_add_i32 s1, 0, 0x25400
	v_mov_b32_e32 v0, s1
	s_waitcnt vmcnt(0) expcnt(0) lgkmcnt(0)
	ds_read_b32 v2, v0
	s_add_i32 s1, 0, 0x25404
	v_mov_b32_e32 v0, s1
	ds_read_b32 v0, v0
	s_waitcnt lgkmcnt(1)
	v_cmp_ne_u32_e32 vcc, 0, v2
	s_cbranch_vccnz .LBB0_1394
	v_readlane_b32 s6, v255, 0
	v_readlane_b32 s7, v255, 1
	s_load_dwordx2 s[2:3], s[6:7], 0x4
	s_add_u32 s6, s82, 0x1000
	s_addc_u32 s7, s83, 0
	s_add_u32 s8, s82, 0x1100
	s_addc_u32 s9, s83, 0
	s_add_u32 s12, s82, 0x1200
	s_addc_u32 s13, s83, 0
	s_waitcnt lgkmcnt(0)
	s_mul_i32 s1, s2, s0
	s_add_u32 s14, s82, 0x1300
	s_mul_i32 s1, s1, s3
	s_addc_u32 s15, s83, 0
	s_mov_b32 s2, 1
	v_mov_b32_e32 v16, 0
	s_branch .LBB0_1382

.LBB0_1409:
	s_or_b64 exec, exec, s[12:13]
	s_waitcnt vmcnt(0)
	s_waitcnt vmcnt(0)

.LBB0_1427:
	s_or_b64 exec, exec, s[8:9]
	s_mov_b64 s[8:9], exec
	v_mbcnt_lo_u32_b32 v0, s8, 0
	v_mbcnt_hi_u32_b32 v0, s9, v0
	v_cmp_eq_u32_e32 vcc, 0, v0
	s_waitcnt vmcnt(0)
	s_and_saveexec_b64 s[12:13], vcc
	s_cbranch_execz .LBB0_1429
	s_bcnt1_i32_b64 s1, s[8:9]
	v_mov_b32_e32 v0, 0x2000
	v_mov_b32_e32 v1, s1
	global_atomic_add v0, v1, s[6:7] offset:1024

.LBB0_1601:
	v_writelane_b32 v255, s58, 7
	s_nop 1
	v_writelane_b32 v255, s59, 8
	s_or_b64 exec, exec, s[4:5]
	s_waitcnt vmcnt(0)
	s_waitcnt lgkmcnt(0)
	s_barrier
	s_mov_b64 s[4:5], exec
	v_readlane_b32 s2, v255, 4
	v_readlane_b32 s3, v255, 5
	s_and_b64 s[2:3], s[4:5], s[2:3]
	s_mov_b64 exec, s[2:3]
	s_cbranch_execnz .Lmy_bar14_t0
	s_cmp_eq_u32 s33, 64
	s_cbranch_scc0 .LBB0_1653
	s_mov_b64 exec, 1
	buffer_inv sc1
	s_waitcnt vmcnt(0)
	s_branch .LBB0_1653

.LBB0_1916:
	s_waitcnt vmcnt(0)
	s_waitcnt vmcnt(0) lgkmcnt(0)
	s_barrier
	s_mov_b64 s[4:5], exec
	v_readlane_b32 s6, v255, 4
	v_readlane_b32 s7, v255, 5
	s_and_b64 s[6:7], s[4:5], s[6:7]
	s_mov_b64 exec, s[6:7]
	s_cbranch_execnz .Lmy_bar15_t0
	s_cmp_eq_u32 s33, 64
	s_cbranch_scc0 .LBB0_1968
	s_mov_b64 exec, 1
	buffer_inv sc1
	s_waitcnt vmcnt(0)
	s_branch .LBB0_1968
.Lmy_bar15_t0:
	s_add_i32 s1, 0, 0x25400
	v_mov_b32_e32 v0, s1
	s_waitcnt vmcnt(0) expcnt(0) lgkmcnt(0)
	ds_read_b32 v2, v0
	s_add_i32 s1, 0, 0x25404
	v_mov_b32_e32 v0, s1
	ds_read_b32 v0, v0
	s_waitcnt lgkmcnt(1)
	v_cmp_ne_u32_e32 vcc, 0, v2
	s_cbranch_vccnz .LBB0_1932
	v_readlane_b32 s6, v255, 0
	v_readlane_b32 s7, v255, 1
	s_load_dwordx2 s[12:13], s[6:7], 0x4
	s_add_u32 s6, s82, 0x1000
	s_addc_u32 s7, s83, 0
	s_add_u32 s8, s82, 0x1100
	s_addc_u32 s9, s83, 0
	s_waitcnt lgkmcnt(0)
	s_mul_i32 s1, s12, s0
	s_add_u32 s12, s82, 0x1200
	s_mul_i32 s1, s1, s13
	s_addc_u32 s13, s83, 0
	s_add_u32 s14, s82, 0x1300
	s_addc_u32 s15, s83, 0
	s_mov_b32 s2, 1
	v_mov_b32_e32 v16, 0
	s_branch .LBB0_1920

.LBB0_2573:
	s_waitcnt vmcnt(0)
	s_waitcnt vmcnt(0)
	s_barrier
	s_mov_b64 s[4:5], exec
	v_readlane_b32 s2, v255, 4
	v_readlane_b32 s3, v255, 5
	s_and_b64 s[2:3], s[4:5], s[2:3]
	s_mov_b64 exec, s[2:3]
	s_cbranch_execnz .Lmy_bar18_t0
	s_cmp_eq_u32 s33, 64
	s_cbranch_scc0 .LBB0_2625
	s_mov_b64 exec, 1
	buffer_inv sc1
	s_waitcnt vmcnt(0)
	s_branch .LBB0_2625

.LBB0_3103:
	v_writelane_b32 v255, s62, 7
	s_nop 1
	v_writelane_b32 v255, s63, 8
	s_or_b64 exec, exec, s[4:5]
	s_waitcnt vmcnt(0)
	s_waitcnt lgkmcnt(0)
	s_barrier
	s_mov_b64 s[4:5], exec
	v_readlane_b32 s2, v255, 4
	v_readlane_b32 s3, v255, 5
	s_and_b64 s[2:3], s[4:5], s[2:3]
	s_mov_b64 exec, s[2:3]
	s_cbranch_execnz .Lmy_bar24_t0
	s_cmp_eq_u32 s33, 64
	s_cbranch_scc0 .LBB0_3155
	s_mov_b64 exec, 1
	buffer_inv sc1
	s_waitcnt vmcnt(0)
	s_branch .LBB0_3155

.LBB0_4294:
	s_waitcnt vmcnt(0)
	s_waitcnt vmcnt(0) lgkmcnt(0)
	s_barrier
	s_mov_b64 s[2:3], exec
	v_readlane_b32 s4, v255, 4
	v_readlane_b32 s5, v255, 5
	s_and_b64 s[4:5], s[2:3], s[4:5]
	s_mov_b64 exec, s[4:5]
	s_cbranch_execnz .Lmy_bar32_t0
	s_cmp_eq_u32 s33, 64
	s_cbranch_scc0 .LBB0_4346
	s_mov_b64 exec, 1
	buffer_inv sc1
	s_waitcnt vmcnt(0)
	s_branch .LBB0_4346
.Lmy_bar32_t0:
	s_add_i32 s1, 0, 0x25400
	v_mov_b32_e32 v0, s1
	s_waitcnt vmcnt(0) expcnt(0) lgkmcnt(0)
	ds_read_b32 v2, v0
	s_add_i32 s1, 0, 0x25404
	v_mov_b32_e32 v0, s1
	ds_read_b32 v0, v0
	s_waitcnt lgkmcnt(1)
	v_cmp_ne_u32_e32 vcc, 0, v2
	s_cbranch_vccnz .LBB0_4310
	v_readlane_b32 s4, v255, 0
	v_readlane_b32 s5, v255, 1
	s_load_dwordx2 s[8:9], s[4:5], 0x4
	s_add_u32 s4, s82, 0x1000
	s_addc_u32 s5, s83, 0
	s_add_u32 s6, s82, 0x1100
	s_addc_u32 s7, s83, 0
	s_waitcnt lgkmcnt(0)
	s_mul_i32 s1, s8, s0
	s_add_u32 s8, s82, 0x1200
	s_mul_i32 s1, s1, s9
	s_addc_u32 s9, s83, 0
	s_add_u32 s10, s82, 0x1300
	s_addc_u32 s11, s83, 0
	s_mov_b32 s18, 1
	v_mov_b32_e32 v16, 0
	s_branch .LBB0_4298

.LBB0_4325:
	s_or_b64 exec, exec, s[8:9]
	s_waitcnt vmcnt(0)
	s_waitcnt vmcnt(0)

.LBB0_4343:
	s_or_b64 exec, exec, s[6:7]
	s_mov_b64 s[6:7], exec
	v_mbcnt_lo_u32_b32 v0, s6, 0
	v_mbcnt_hi_u32_b32 v0, s7, v0
	v_cmp_eq_u32_e32 vcc, 0, v0
	s_waitcnt vmcnt(0)
	s_and_saveexec_b64 s[8:9], vcc
	s_cbranch_execz .LBB0_4345
	s_bcnt1_i32_b64 s1, s[6:7]
	v_mov_b32_e32 v0, 0x2000
	v_mov_b32_e32 v1, s1
	global_atomic_add v0, v1, s[4:5] offset:1024
